# v_tail3 + lambda parameters prefetched by LDS-DMA at P1 start (removes a cold global-load latency at P2 start)
# baseline (speedup 1.0000x reference)
.LBB0_191:
	s_or_b64 exec, exec, s[4:5]
	s_load_dwordx16 s[16:31], s[0:1], 0x40
	s_waitcnt lgkmcnt(0)
	v_readfirstlane_b32 s98, v215
	v_and_b32_e32 v1, 63, v215
	v_lshlrev_b32_e32 v1, 2, v1
	s_nop 1
	s_lshr_b32 s98, s98, 6
	s_lshl_b32 s98, s98, 10
	s_add_i32 s98, s98, 0x20000
	s_mov_b32 m0, s98
	s_nop 0
	global_load_lds_dword v1, s[48:49]
	s_add_i32 m0, s98, 0x100
	s_nop 0
	global_load_lds_dword v1, s[50:51]
	s_add_i32 m0, s98, 0x200
	s_nop 0
	global_load_lds_dword v1, s[16:17]
	s_add_i32 m0, s98, 0x300
	s_nop 0
	global_load_lds_dword v1, s[18:19]
	s_cmpk_lt_i32 s88, 0x500
	v_mov_b32_e32 v0, v215
	s_waitcnt vmcnt(5)
	v_mov_b32_e32 v8, v215
	s_barrier
	s_cselect_b64 s[4:5], -1, 0
	s_cmpk_gt_i32 s88, 0x4ff
	s_nop 0
	v_readfirstlane_b32 s2, v8
	s_cbranch_scc1 .LBB0_193
	s_ashr_i32 s0, s88, 31
	s_lshr_b32 s0, s0, 29
	s_add_i32 s0, s88, s0
	s_ashr_i32 s1, s0, 3
	s_and_b32 s0, s0, -8
	s_sub_i32 s0, s88, s0
	s_cmp_lt_i32 s0, 0
	s_movk_i32 s3, 0xa1
	s_cselect_b32 s3, s3, 0xa0
	s_mul_i32 s0, s0, s3
	s_add_i32 s0, s0, s1
	s_mul_hi_i32 s1, s0, 0x66666667
	s_lshr_b32 s3, s1, 31
	s_ashr_i32 s1, s1, 4
	s_add_i32 s1, s1, s3
	s_lshl_b32 s3, s1, 2
	s_mul_i32 s1, s1, 40
	s_sub_i32 s0, s0, s1
	s_bfe_i32 s1, s0, 0x80000
	s_bfe_u32 s1, s1, 0x2000d
	s_add_i32 s1, s0, s1
	s_bfe_i32 s6, s1, 0x80000
	s_and_b32 s1, s1, 0xfc
	s_sub_i32 s0, s0, s1
	s_sext_i32_i16 s6, s6
	s_sext_i32_i8 s0, s0
	s_add_i32 s0, s3, s0
	s_ashr_i32 s64, s6, 2

.LBB0_389:
	v_writelane_b32 v254, s91, 21
	v_writelane_b32 v254, s92, 22
	s_nop 1
	v_writelane_b32 v254, s93, 23
	v_writelane_b32 v254, s90, 24
	v_writelane_b32 v254, s88, 25
	s_nop 1
	v_writelane_b32 v254, s89, 26
	s_or_b64 exec, exec, s[0:1]
	s_waitcnt lgkmcnt(0)
	v_mov_b32_e32 v0, v215
	s_barrier
	v_and_b32_e32 v4, 64, v34
	v_and_b32_e32 v0, 63, v0
	v_lshlrev_b32_e32 v0, 2, v0
	v_lshrrev_b32_e32 v5, 6, v215
	v_lshlrev_b32_e32 v5, 10, v5
	v_add_u32_e32 v5, 0x20000, v5
	v_add_u32_e32 v5, v5, v0
	ds_read_b32 v1, v5
	ds_read_b32 v2, v5 offset:256
	ds_read_b32 v3, v5 offset:512
	ds_read_b32 v0, v5 offset:768
	v_xor_b32_e32 v5, 1, v34
	v_add_u32_e32 v4, 64, v4
	v_cmp_lt_i32_e32 vcc, v5, v4
	v_xor_b32_e32 v6, 2, v34
	v_xor_b32_e32 v7, 4, v34
	v_cndmask_b32_e32 v5, v34, v5, vcc
	v_lshlrev_b32_e32 v212, 2, v5
	v_cmp_lt_i32_e32 vcc, v6, v4
	v_xor_b32_e32 v8, 8, v34
	v_xor_b32_e32 v9, 16, v34
	v_cndmask_b32_e32 v6, v34, v6, vcc
	v_lshlrev_b32_e32 v213, 2, v6
	v_cmp_lt_i32_e32 vcc, v7, v4
	v_xor_b32_e32 v10, 32, v34
	s_add_u32 s92, s62, 0x5c00000
	s_addc_u32 s93, s63, 0
	s_cmpk_gt_i32 s33, 0xff
	s_mov_b32 s7, 0
	s_waitcnt lgkmcnt(2)
	v_mul_f32_e32 v5, v1, v2
	ds_bpermute_b32 v5, v212, v5
	s_waitcnt lgkmcnt(1)
	v_mul_f32_e32 v11, v3, v0
	ds_bpermute_b32 v11, v212, v11
	s_waitcnt lgkmcnt(1)
	v_fmac_f32_e32 v5, v1, v2
	v_cndmask_b32_e32 v2, v34, v7, vcc
	s_waitcnt lgkmcnt(0)
	v_fmac_f32_e32 v11, v3, v0
	ds_bpermute_b32 v0, v213, v5
	ds_bpermute_b32 v1, v213, v11
	v_lshlrev_b32_e32 v214, 2, v2
	v_cmp_lt_i32_e32 vcc, v8, v4
	s_waitcnt lgkmcnt(1)
	v_add_f32_e32 v0, v5, v0
	s_waitcnt lgkmcnt(0)
	v_add_f32_e32 v1, v11, v1
	ds_bpermute_b32 v2, v214, v0
	ds_bpermute_b32 v3, v214, v1
	v_cndmask_b32_e32 v5, v34, v8, vcc
	v_lshlrev_b32_e32 v216, 2, v5
	v_cmp_lt_i32_e32 vcc, v9, v4
	s_waitcnt lgkmcnt(1)
	v_add_f32_e32 v0, v0, v2
	s_waitcnt lgkmcnt(0)
	v_add_f32_e32 v1, v1, v3
	ds_bpermute_b32 v2, v216, v0
	ds_bpermute_b32 v3, v216, v1
	v_cndmask_b32_e32 v5, v34, v9, vcc
	v_lshlrev_b32_e32 v219, 2, v5
	v_cmp_lt_i32_e32 vcc, v10, v4
	s_waitcnt lgkmcnt(1)
	v_add_f32_e32 v0, v0, v2
	s_waitcnt lgkmcnt(0)
	v_add_f32_e32 v1, v1, v3
	ds_bpermute_b32 v2, v219, v0
	ds_bpermute_b32 v3, v219, v1
	v_cndmask_b32_e32 v4, v34, v10, vcc
	v_lshlrev_b32_e32 v223, 2, v4
	s_waitcnt lgkmcnt(1)
	v_add_f32_e32 v0, v0, v2
	s_waitcnt lgkmcnt(0)
	v_add_f32_e32 v1, v1, v3
	ds_bpermute_b32 v2, v223, v0
	ds_bpermute_b32 v3, v223, v1
	s_cbranch_scc1 .LBB0_483
	s_waitcnt lgkmcnt(1)
	v_add_f32_e32 v0, v0, v2
	s_waitcnt lgkmcnt(0)
	v_add_f32_e32 v1, v1, v3
	v_mul_f32_e32 v0, 0x3fb8aa3b, v0
	v_mul_f32_e32 v1, 0x3fb8aa3b, v1
	v_exp_f32_e32 v0, v0
	v_exp_f32_e32 v1, v1
	s_add_u32 s0, s62, 0xde00000
	v_writelane_b32 v254, s0, 27
	s_addc_u32 s0, s63, 0
	v_writelane_b32 v254, s0, 28
	v_sub_f32_e32 v0, v0, v1
	v_add_f32_e32 v217, 0x3e4ccccd, v0
	v_mov_b32_e32 v205, 0
	s_mov_b64 s[8:9], 0x80
	s_mov_b64 s[12:13], 0x10000
	s_mov_b64 s[16:17], 0x20000
	s_mov_b64 s[18:19], 0x30000
	s_mov_b64 s[70:71], 0x10080
	s_mov_b64 s[72:73], 0x40000
	s_mov_b64 s[74:75], 0x11f20000
	s_mov_b64 s[76:77], 0x11f20080
	s_mov_b64 s[78:79], 0x50000
	s_mov_b64 s[80:81], 0x11f30000
	s_mov_b64 s[82:83], 0x11f30080
	s_mov_b64 s[84:85], 0x11f10000
	s_mov_b64 s[86:87], 0x11f10080
	v_mov_b32_e32 v218, 0x358637bd
	v_mov_b32_e32 v220, 0xff800000
	v_writelane_b32 v254, s92, 29
	v_writelane_b32 v254, s93, 30
	s_branch .LBB0_392
